# all 8 waves of an idle workgroup convert stolen weight tiles (NSTEAL 4 to 8) on top of ph3 reassign and attention vmcnt fix
# speedup vs baseline: 1.0067x; 1.0067x over previous
; #define LAS __attribute__((address_space(3)))
; __device__ __forceinline__ int otid() { int t = threadIdx.x; asm volatile("" : "+v"(t)); return t; }
; __device__ __forceinline__ void transpose_item(const float* __restrict__ src, int ldn, int k0, int n0, bf16_t* __restrict__ dst, int Kd, int drow, LAS float* scr, int lane) {
;     const int cl = (lane & 15) * 4, ks = lane >> 4;
;     f32x4 v[16];
; #pragma unroll
;     for (int i = 0; i < 16; ++i) v[i] = __builtin_nontemporal_load((const f32x4*)(src + (size_t)(k0 + 4 * i + ks) * ldn + n0 + cl));
; #pragma unroll
;     for (int i = 0; i < 16; ++i) { LAS float* s = scr + (4 * i + ks) * 65 + cl; s[0] = v[i][0]; s[1] = v[i][1]; s[2] = v[i][2]; s[3] = v[i][3]; }
;     asm volatile("s_waitcnt lgkmcnt(0)" ::: "memory");
;     const int c = lane & 7;
; #pragma unroll
;     for (int j = 0; j < 8; ++j) { const int n = (lane >> 3) + 8 * j; const LAS float* s = scr + (8 * c) * 65 + n;
;     const int tid = otid(), w = __builtin_amdgcn_readfirstlane(tid >> 6), lane = tid & 63;
;     LAS float* scr = (LAS float*)lds + w * (64 * 65);
;     volatile LAS int* bc = (volatile LAS int*)(lds + LDS_BYTES - 32);
;     const int n = n1 + n2 + n3;
;     for (;;) {
;         __syncthreads();
;         if (tid == 0) bc[0] = (int)__hip_atomic_fetch_add(ctr, (unsigned)NSTEAL, __ATOMIC_RELAXED, __HIP_MEMORY_SCOPE_AGENT);
;         __syncthreads();
;         const int base = bc[0];
;         if (base >= n) break;
;         const int j = base + w;
;         if (w < NSTEAL && j < n) convert_item(a, j < n1 ? lo1 + j : (j < n1 + n2 ? lo2 + (j - n1) : lo3 + (j - n1 - n2)), scr, lane);
.LBB0_181:
	v_mov_b32_e32 v1, v169
	s_nop 0
	v_readfirstlane_b32 s4, v1
	s_ashr_i32 s4, s4, 6
	s_mul_i32 s6, s4, 0x4100
	v_cmp_eq_u32_e64 s[38:39], 0, v1
	v_lshlrev_b32_e32 v0, 2, v1
	v_bfe_u32 v2, v1, 4, 2
	v_bfe_u32 v3, v1, 3, 3
	v_lshlrev_b32_e32 v1, 3, v1
	s_add_i32 s8, s6, 0
	v_and_b32_e32 v0, 60, v0
	v_and_b32_e32 v14, 56, v1
	s_cmp_lt_i32 s4, 8
	v_lshl_add_u32 v12, v0, 2, s8
	v_mul_u32_u24_e32 v13, 0x104, v2
	v_mul_u32_u24_e32 v1, 0x104, v14
	v_lshlrev_b32_e32 v4, 2, v3
	s_cselect_b64 s[6:7], -1, 0
	v_add3_u32 v4, s8, v1, v4
	v_or_b32_e32 v5, 8, v3
	v_or_b32_e32 v6, 16, v3
	v_or_b32_e32 v7, 24, v3
	v_or_b32_e32 v8, 32, v3
	v_or_b32_e32 v9, 40, v3
	v_or_b32_e32 v10, 48, v3
	v_or_b32_e32 v11, 56, v3
	v_lshlrev_b32_e32 v152, 2, v0
	v_add_u32_e32 v12, v12, v13
	v_lshlrev_b32_e32 v0, 1, v14
	s_branch .LBB0_187

;     ...
;     for (;;) {
;         __syncthreads();
;         if (tid == 0) bc[0] = (int)__hip_atomic_fetch_add(ctr, (unsigned)NSTEAL, __ATOMIC_RELAXED, __HIP_MEMORY_SCOPE_AGENT);
;         __syncthreads();
;         const int base = bc[0];
.LBB0_187:
	s_waitcnt vmcnt(63) expcnt(7) lgkmcnt(15)
	s_barrier
	s_and_saveexec_b64 s[8:9], s[38:39]
	s_cbranch_execz .LBB0_191
	s_mov_b64 s[12:13], exec
	v_mbcnt_lo_u32_b32 v1, s12, 0
	v_mbcnt_hi_u32_b32 v1, s13, v1
	v_cmp_eq_u32_e32 vcc, 0, v1
	s_and_saveexec_b64 s[10:11], vcc
	s_cbranch_execz .LBB0_190
	s_bcnt1_i32_b64 s12, s[12:13]
	s_lshl_b32 s12, s12, 3
	v_mov_b32_e32 v13, s12
	v_readlane_b32 s12, v248, 56
	v_readlane_b32 s13, v248, 57
	s_nop 4
	global_atomic_add v13, v153, v13, s[12:13] sc0
.LBB0_190:
	s_or_b64 exec, exec, s[10:11]
	s_waitcnt vmcnt(0)
	v_readfirstlane_b32 s10, v13
	v_mov_b32_e32 v13, s23
	s_nop 0
	v_lshl_add_u32 v1, v1, 3, s10
	ds_write_b32 v13, v1

;     ...
;     for (;;) {
;         __syncthreads();
;         if (tid == 0) bc[0] = (int)__hip_atomic_fetch_add(ctr, (unsigned)NSTEAL, __ATOMIC_RELAXED, __HIP_MEMORY_SCOPE_AGENT);
;         __syncthreads();
;         const int base = bc[0];
.LBB0_210:
	s_barrier
	s_and_saveexec_b64 s[8:9], s[38:39]
	s_cbranch_execz .LBB0_214
	s_mov_b64 s[12:13], exec
	v_mbcnt_lo_u32_b32 v1, s12, 0
	v_mbcnt_hi_u32_b32 v1, s13, v1
	v_cmp_eq_u32_e32 vcc, 0, v1
	s_and_saveexec_b64 s[10:11], vcc
	s_cbranch_execz .LBB0_213
	s_bcnt1_i32_b64 s12, s[12:13]
	s_lshl_b32 s12, s12, 3
	v_mov_b32_e32 v13, s12
	v_readlane_b32 s12, v248, 62
	v_readlane_b32 s13, v248, 63
	s_nop 4
	global_atomic_add v13, v153, v13, s[12:13] sc0

; #define LAS __attribute__((address_space(3)))
; __device__ __forceinline__ int otid() { int t = threadIdx.x; asm volatile("" : "+v"(t)); return t; }
; __device__ __forceinline__ void transpose_item(const float* __restrict__ src, int ldn, int k0, int n0, bf16_t* __restrict__ dst, int Kd, int drow, LAS float* scr, int lane) {
;     const int cl = (lane & 15) * 4, ks = lane >> 4;
;     f32x4 v[16];
; #pragma unroll
;     for (int i = 0; i < 16; ++i) v[i] = __builtin_nontemporal_load((const f32x4*)(src + (size_t)(k0 + 4 * i + ks) * ldn + n0 + cl));
; #pragma unroll
;     for (int i = 0; i < 16; ++i) { LAS float* s = scr + (4 * i + ks) * 65 + cl; s[0] = v[i][0]; s[1] = v[i][1]; s[2] = v[i][2]; s[3] = v[i][3]; }
;     asm volatile("s_waitcnt lgkmcnt(0)" ::: "memory");
;     const int c = lane & 7;
; #pragma unroll
;     for (int j = 0; j < 8; ++j) { const int n = (lane >> 3) + 8 * j; const LAS float* s = scr + (8 * c) * 65 + n;
;     const int tid = otid(), w = __builtin_amdgcn_readfirstlane(tid >> 6), lane = tid & 63;
;     LAS float* scr = (LAS float*)lds + w * (64 * 65);
;     volatile LAS int* bc = (volatile LAS int*)(lds + LDS_BYTES - 32);
;     const int n = n1 + n2 + n3;
;     for (;;) {
;         __syncthreads();
;         if (tid == 0) bc[0] = (int)__hip_atomic_fetch_add(ctr, (unsigned)NSTEAL, __ATOMIC_RELAXED, __HIP_MEMORY_SCOPE_AGENT);
;         __syncthreads();
;         const int base = bc[0];
;         if (base >= n) break;
;         const int j = base + w;
;         if (w < NSTEAL && j < n) convert_item(a, j < n1 ? lo1 + j : (j < n1 + n2 ? lo2 + (j - n1) : lo3 + (j - n1 - n2)), scr, lane);
.LBB0_242:
	v_mov_b32_e32 v1, v169
	s_nop 0
	v_readfirstlane_b32 s4, v1
	s_ashr_i32 s4, s4, 6
	s_mul_i32 s6, s4, 0x4100
	v_cmp_eq_u32_e64 s[38:39], 0, v1
	v_lshlrev_b32_e32 v0, 2, v1
	v_bfe_u32 v2, v1, 4, 2
	v_bfe_u32 v3, v1, 3, 3
	v_lshlrev_b32_e32 v1, 3, v1
	s_add_i32 s8, s6, 0
	v_and_b32_e32 v0, 60, v0
	v_and_b32_e32 v14, 56, v1
	s_cmp_lt_i32 s4, 8
	v_lshl_add_u32 v12, v0, 2, s8
	s_waitcnt lgkmcnt(0)
	v_mul_u32_u24_e32 v13, 0x104, v2
	v_mul_u32_u24_e32 v1, 0x104, v14
	v_lshlrev_b32_e32 v4, 2, v3
	s_cselect_b64 s[6:7], -1, 0
	v_add3_u32 v4, s8, v1, v4
	v_or_b32_e32 v5, 8, v3
	v_or_b32_e32 v6, 16, v3
	v_or_b32_e32 v7, 24, v3
	v_or_b32_e32 v8, 32, v3
	v_or_b32_e32 v9, 40, v3
	v_or_b32_e32 v10, 48, v3
	v_or_b32_e32 v11, 56, v3
	v_lshlrev_b32_e32 v152, 2, v0
	v_add_u32_e32 v12, v12, v13
	v_lshlrev_b32_e32 v0, 1, v14
	s_branch .LBB0_248

;     ...
;     for (;;) {
;         __syncthreads();
;         if (tid == 0) bc[0] = (int)__hip_atomic_fetch_add(ctr, (unsigned)NSTEAL, __ATOMIC_RELAXED, __HIP_MEMORY_SCOPE_AGENT);
;         __syncthreads();
;         const int base = bc[0];
.LBB0_248:
	s_waitcnt vmcnt(0)
	s_barrier
	s_and_saveexec_b64 s[8:9], s[38:39]
	s_cbranch_execz .LBB0_252
	s_mov_b64 s[12:13], exec
	v_mbcnt_lo_u32_b32 v1, s12, 0
	v_mbcnt_hi_u32_b32 v1, s13, v1
	v_cmp_eq_u32_e32 vcc, 0, v1
	s_and_saveexec_b64 s[10:11], vcc
	s_cbranch_execz .LBB0_251
	s_bcnt1_i32_b64 s12, s[12:13]
	s_lshl_b32 s12, s12, 3
	v_mov_b32_e32 v13, s12
	v_readlane_b32 s12, v247, 2
	v_readlane_b32 s13, v247, 3
	s_nop 4
	global_atomic_add v13, v153, v13, s[12:13] sc0

; #define LAS __attribute__((address_space(3)))
; __device__ __forceinline__ int otid() { int t = threadIdx.x; asm volatile("" : "+v"(t)); return t; }
; __device__ __forceinline__ void transpose_item(const float* __restrict__ src, int ldn, int k0, int n0, bf16_t* __restrict__ dst, int Kd, int drow, LAS float* scr, int lane) {
;     const int cl = (lane & 15) * 4, ks = lane >> 4;
;     f32x4 v[16];
; #pragma unroll
;     for (int i = 0; i < 16; ++i) v[i] = __builtin_nontemporal_load((const f32x4*)(src + (size_t)(k0 + 4 * i + ks) * ldn + n0 + cl));
; #pragma unroll
;     for (int i = 0; i < 16; ++i) { LAS float* s = scr + (4 * i + ks) * 65 + cl; s[0] = v[i][0]; s[1] = v[i][1]; s[2] = v[i][2]; s[3] = v[i][3]; }
;     asm volatile("s_waitcnt lgkmcnt(0)" ::: "memory");
;     const int c = lane & 7;
; #pragma unroll
;     for (int j = 0; j < 8; ++j) { const int n = (lane >> 3) + 8 * j; const LAS float* s = scr + (8 * c) * 65 + n;
;     const int tid = otid(), w = __builtin_amdgcn_readfirstlane(tid >> 6), lane = tid & 63;
;     LAS float* scr = (LAS float*)lds + w * (64 * 65);
;     volatile LAS int* bc = (volatile LAS int*)(lds + LDS_BYTES - 32);
;     const int n = n1 + n2 + n3;
;     for (;;) {
;         __syncthreads();
;         if (tid == 0) bc[0] = (int)__hip_atomic_fetch_add(ctr, (unsigned)NSTEAL, __ATOMIC_RELAXED, __HIP_MEMORY_SCOPE_AGENT);
;         __syncthreads();
;         const int base = bc[0];
;         if (base >= n) break;
;         const int j = base + w;
;         if (w < NSTEAL && j < n) convert_item(a, j < n1 ? lo1 + j : (j < n1 + n2 ? lo2 + (j - n1) : lo3 + (j - n1 - n2)), scr, lane);
.LBB0_362:
	v_readlane_b32 s8, v246, 46
	v_readlane_b32 s9, v246, 47
	v_readlane_b32 s48, v246, 54
	s_andn2_b64 vcc, exec, s[8:9]
	v_readlane_b32 s49, v246, 55
	v_readlane_b32 s50, v246, 56
	v_readlane_b32 s51, v246, 57
	v_readlane_b32 s52, v246, 58
	v_readlane_b32 s53, v246, 59
	v_readlane_b32 s54, v246, 60
	v_readlane_b32 s55, v246, 61
	v_readlane_b32 s56, v246, 62
	v_readlane_b32 s57, v246, 63
	v_readlane_b32 s58, v219, 0
	v_readlane_b32 s59, v219, 1
	v_readlane_b32 s60, v219, 2
	v_readlane_b32 s61, v219, 3
	v_readlane_b32 s62, v219, 4
	v_readlane_b32 s63, v219, 5
	s_cbranch_vccnz .LBB0_402
	v_mov_b32_e32 v1, v169
	s_nop 0
	v_readfirstlane_b32 s4, v1
	s_ashr_i32 s4, s4, 6
	s_mul_i32 s8, s4, 0x4100
	v_cmp_eq_u32_e64 s[38:39], 0, v1
	v_lshlrev_b32_e32 v0, 2, v1
	v_bfe_u32 v2, v1, 4, 2
	v_bfe_u32 v3, v1, 3, 3
	v_lshlrev_b32_e32 v1, 3, v1
	s_add_i32 s10, s8, 0
	v_and_b32_e32 v0, 60, v0
	v_and_b32_e32 v14, 56, v1
	s_cmp_lt_i32 s4, 8
	v_lshl_add_u32 v12, v0, 2, s10
	s_waitcnt lgkmcnt(0)
	v_mul_u32_u24_e32 v13, 0x104, v2
	v_mul_u32_u24_e32 v1, 0x104, v14
	v_lshlrev_b32_e32 v4, 2, v3
	s_cselect_b64 s[8:9], -1, 0
	v_add3_u32 v4, s10, v1, v4
	v_or_b32_e32 v5, 8, v3
	v_or_b32_e32 v6, 16, v3
	v_or_b32_e32 v7, 24, v3
	v_or_b32_e32 v8, 32, v3
	v_or_b32_e32 v9, 40, v3
	v_or_b32_e32 v10, 48, v3
	v_or_b32_e32 v11, 56, v3
	v_lshlrev_b32_e32 v152, 2, v0
	v_add_u32_e32 v12, v12, v13
	v_lshlrev_b32_e32 v0, 1, v14
	s_branch .LBB0_368

;     ...
;     for (;;) {
;         __syncthreads();
;         if (tid == 0) bc[0] = (int)__hip_atomic_fetch_add(ctr, (unsigned)NSTEAL, __ATOMIC_RELAXED, __HIP_MEMORY_SCOPE_AGENT);
;         __syncthreads();
;         const int base = bc[0];
.LBB0_368:
	s_waitcnt vmcnt(0)
	s_barrier
	s_and_saveexec_b64 s[10:11], s[38:39]
	s_cbranch_execz .LBB0_372
	s_mov_b64 s[14:15], exec
	v_mbcnt_lo_u32_b32 v1, s14, 0
	v_mbcnt_hi_u32_b32 v1, s15, v1
	v_cmp_eq_u32_e32 vcc, 0, v1
	s_and_saveexec_b64 s[12:13], vcc
	s_cbranch_execz .LBB0_371
	s_bcnt1_i32_b64 s14, s[14:15]
	s_lshl_b32 s14, s14, 3
	v_mov_b32_e32 v13, s14
	v_readlane_b32 s14, v247, 10
	v_readlane_b32 s15, v247, 11
	s_nop 4
	global_atomic_add v13, v153, v13, s[14:15] sc0
.LBB0_371:
	s_or_b64 exec, exec, s[12:13]
	s_waitcnt vmcnt(0)
	v_readfirstlane_b32 s12, v13
	v_mov_b32_e32 v13, s23
	s_nop 0
	v_lshl_add_u32 v1, v1, 3, s12
	ds_write_b32 v13, v1

; #define LAS __attribute__((address_space(3)))
; __device__ __forceinline__ int otid() { int t = threadIdx.x; asm volatile("" : "+v"(t)); return t; }
; __device__ __forceinline__ void transpose_item(const float* __restrict__ src, int ldn, int k0, int n0, bf16_t* __restrict__ dst, int Kd, int drow, LAS float* scr, int lane) {
;     const int cl = (lane & 15) * 4, ks = lane >> 4;
;     f32x4 v[16];
; #pragma unroll
;     for (int i = 0; i < 16; ++i) v[i] = __builtin_nontemporal_load((const f32x4*)(src + (size_t)(k0 + 4 * i + ks) * ldn + n0 + cl));
; #pragma unroll
;     for (int i = 0; i < 16; ++i) { LAS float* s = scr + (4 * i + ks) * 65 + cl; s[0] = v[i][0]; s[1] = v[i][1]; s[2] = v[i][2]; s[3] = v[i][3]; }
;     asm volatile("s_waitcnt lgkmcnt(0)" ::: "memory");
;     const int c = lane & 7;
; #pragma unroll
;     for (int j = 0; j < 8; ++j) { const int n = (lane >> 3) + 8 * j; const LAS float* s = scr + (8 * c) * 65 + n;
;     const int tid = otid(), w = __builtin_amdgcn_readfirstlane(tid >> 6), lane = tid & 63;
;     LAS float* scr = (LAS float*)lds + w * (64 * 65);
;     volatile LAS int* bc = (volatile LAS int*)(lds + LDS_BYTES - 32);
;     const int n = n1 + n2 + n3;
;     for (;;) {
;         __syncthreads();
;         if (tid == 0) bc[0] = (int)__hip_atomic_fetch_add(ctr, (unsigned)NSTEAL, __ATOMIC_RELAXED, __HIP_MEMORY_SCOPE_AGENT);
;         __syncthreads();
;         const int base = bc[0];
;         if (base >= n) break;
;         const int j = base + w;
;         if (w < NSTEAL && j < n) convert_item(a, j < n1 ? lo1 + j : (j < n1 + n2 ? lo2 + (j - n1) : lo3 + (j - n1 - n2)), scr, lane);
.LBB0_443:
	v_readlane_b32 s48, v246, 54
	s_mov_b64 s[12:13], -1
	s_and_b64 vcc, exec, s[10:11]
	v_readlane_b32 s49, v246, 55
	v_readlane_b32 s50, v246, 56
	v_readlane_b32 s51, v246, 57
	v_readlane_b32 s52, v246, 58
	v_readlane_b32 s53, v246, 59
	v_readlane_b32 s54, v246, 60
	v_readlane_b32 s55, v246, 61
	v_readlane_b32 s56, v246, 62
	v_readlane_b32 s57, v246, 63
	v_readlane_b32 s58, v219, 0
	v_readlane_b32 s59, v219, 1
	v_readlane_b32 s60, v219, 2
	v_readlane_b32 s61, v219, 3
	v_readlane_b32 s62, v219, 4
	v_readlane_b32 s63, v219, 5
	s_cbranch_vccz .LBB0_461
	s_andn2_b64 vcc, exec, s[8:9]
	s_cbranch_vccnz .LBB0_460
	v_mov_b32_e32 v1, v169
	s_nop 0
	v_readfirstlane_b32 s4, v1
	s_ashr_i32 s4, s4, 6
	s_mul_i32 s8, s4, 0x4100
	v_cmp_eq_u32_e64 s[38:39], 0, v1
	v_lshlrev_b32_e32 v0, 2, v1
	v_bfe_u32 v2, v1, 4, 2
	v_bfe_u32 v3, v1, 3, 3
	v_lshlrev_b32_e32 v1, 3, v1
	s_add_i32 s10, s8, 0
	v_and_b32_e32 v0, 60, v0
	v_and_b32_e32 v14, 56, v1
	s_cmp_lt_i32 s4, 8
	v_lshl_add_u32 v12, v0, 2, s10
	s_waitcnt lgkmcnt(0)
	v_mul_u32_u24_e32 v13, 0x104, v2
	v_mul_u32_u24_e32 v1, 0x104, v14
	v_lshlrev_b32_e32 v4, 2, v3
	s_cselect_b64 s[8:9], -1, 0
	v_add3_u32 v4, s10, v1, v4
	v_or_b32_e32 v5, 8, v3
	v_or_b32_e32 v6, 16, v3
	v_or_b32_e32 v7, 24, v3
	v_or_b32_e32 v8, 32, v3
	v_or_b32_e32 v9, 40, v3
	v_or_b32_e32 v10, 48, v3
	v_or_b32_e32 v11, 56, v3
	v_lshlrev_b32_e32 v152, 2, v0
	v_add_u32_e32 v12, v12, v13
	v_lshlrev_b32_e32 v0, 1, v14
	s_branch .LBB0_450

;     ...
;     for (;;) {
;         __syncthreads();
;         if (tid == 0) bc[0] = (int)__hip_atomic_fetch_add(ctr, (unsigned)NSTEAL, __ATOMIC_RELAXED, __HIP_MEMORY_SCOPE_AGENT);
;         __syncthreads();
;         const int base = bc[0];
.LBB0_450:
	s_waitcnt vmcnt(0)
	s_barrier
	s_and_saveexec_b64 s[10:11], s[38:39]
	s_cbranch_execz .LBB0_454
	s_mov_b64 s[14:15], exec
	v_mbcnt_lo_u32_b32 v1, s14, 0
	v_mbcnt_hi_u32_b32 v1, s15, v1
	v_cmp_eq_u32_e32 vcc, 0, v1
	s_and_saveexec_b64 s[12:13], vcc
	s_cbranch_execz .LBB0_453
	s_bcnt1_i32_b64 s14, s[14:15]
	s_lshl_b32 s14, s14, 3
	v_mov_b32_e32 v13, s14
	v_readlane_b32 s14, v248, 38
	v_readlane_b32 s15, v248, 39
	s_nop 4
	global_atomic_add v13, v153, v13, s[14:15] sc0

; #define LAS __attribute__((address_space(3)))
; __device__ __forceinline__ int otid() { int t = threadIdx.x; asm volatile("" : "+v"(t)); return t; }
; __device__ __forceinline__ void transpose_item(const float* __restrict__ src, int ldn, int k0, int n0, bf16_t* __restrict__ dst, int Kd, int drow, LAS float* scr, int lane) {
;     const int cl = (lane & 15) * 4, ks = lane >> 4;
;     f32x4 v[16];
; #pragma unroll
;     for (int i = 0; i < 16; ++i) v[i] = __builtin_nontemporal_load((const f32x4*)(src + (size_t)(k0 + 4 * i + ks) * ldn + n0 + cl));
; #pragma unroll
;     for (int i = 0; i < 16; ++i) { LAS float* s = scr + (4 * i + ks) * 65 + cl; s[0] = v[i][0]; s[1] = v[i][1]; s[2] = v[i][2]; s[3] = v[i][3]; }
;     asm volatile("s_waitcnt lgkmcnt(0)" ::: "memory");
;     const int c = lane & 7;
; #pragma unroll
;     for (int j = 0; j < 8; ++j) { const int n = (lane >> 3) + 8 * j; const LAS float* s = scr + (8 * c) * 65 + n;
;     const int tid = otid(), w = __builtin_amdgcn_readfirstlane(tid >> 6), lane = tid & 63;
;     LAS float* scr = (LAS float*)lds + w * (64 * 65);
;     volatile LAS int* bc = (volatile LAS int*)(lds + LDS_BYTES - 32);
;     const int n = n1 + n2 + n3;
;     for (;;) {
;         __syncthreads();
;         if (tid == 0) bc[0] = (int)__hip_atomic_fetch_add(ctr, (unsigned)NSTEAL, __ATOMIC_RELAXED, __HIP_MEMORY_SCOPE_AGENT);
;         __syncthreads();
;         const int base = bc[0];
;         if (base >= n) break;
;         const int j = base + w;
;         if (w < NSTEAL && j < n) convert_item(a, j < n1 ? lo1 + j : (j < n1 + n2 ? lo2 + (j - n1) : lo3 + (j - n1 - n2)), scr, lane);
.LBB0_461:
	s_andn2_b64 vcc, exec, s[12:13]
	s_cbranch_vccnz .LBB0_477
	v_mov_b32_e32 v1, v169
	s_nop 0
	v_readfirstlane_b32 s4, v1
	s_ashr_i32 s4, s4, 6
	s_mul_i32 s8, s4, 0x4100
	v_cmp_eq_u32_e64 s[38:39], 0, v1
	v_lshlrev_b32_e32 v0, 2, v1
	v_bfe_u32 v2, v1, 4, 2
	v_bfe_u32 v3, v1, 3, 3
	v_lshlrev_b32_e32 v1, 3, v1
	s_add_i32 s10, s8, 0
	v_and_b32_e32 v0, 60, v0
	v_and_b32_e32 v14, 56, v1
	s_cmp_lt_i32 s4, 8
	v_lshl_add_u32 v12, v0, 2, s10
	s_waitcnt lgkmcnt(0)
	v_mul_u32_u24_e32 v13, 0x104, v2
	v_mul_u32_u24_e32 v1, 0x104, v14
	v_lshlrev_b32_e32 v4, 2, v3
	s_cselect_b64 s[8:9], -1, 0
	v_add3_u32 v4, s10, v1, v4
	v_or_b32_e32 v5, 8, v3
	v_or_b32_e32 v6, 16, v3
	v_or_b32_e32 v7, 24, v3
	v_or_b32_e32 v8, 32, v3
	v_or_b32_e32 v9, 40, v3
	v_or_b32_e32 v10, 48, v3
	v_or_b32_e32 v11, 56, v3
	v_lshlrev_b32_e32 v152, 2, v0
	v_add_u32_e32 v12, v12, v13
	v_lshlrev_b32_e32 v0, 1, v14
	s_branch .LBB0_467

;     ...
;     for (;;) {
;         __syncthreads();
;         if (tid == 0) bc[0] = (int)__hip_atomic_fetch_add(ctr, (unsigned)NSTEAL, __ATOMIC_RELAXED, __HIP_MEMORY_SCOPE_AGENT);
;         __syncthreads();
;         const int base = bc[0];
.LBB0_467:
	s_waitcnt vmcnt(0)
	s_barrier
	s_and_saveexec_b64 s[10:11], s[38:39]
	s_cbranch_execz .LBB0_471
	s_mov_b64 s[14:15], exec
	v_mbcnt_lo_u32_b32 v1, s14, 0
	v_mbcnt_hi_u32_b32 v1, s15, v1
	v_cmp_eq_u32_e32 vcc, 0, v1
	s_and_saveexec_b64 s[12:13], vcc
	s_cbranch_execz .LBB0_470
	s_bcnt1_i32_b64 s14, s[14:15]
	s_lshl_b32 s14, s14, 3
	v_mov_b32_e32 v13, s14
	v_readlane_b32 s14, v248, 42
	v_readlane_b32 s15, v248, 43
	s_nop 4
	global_atomic_add v13, v153, v13, s[14:15] sc0
